# scan: second-round remainder items moved to the last 64 virtual blocks (away from the blocks that also run the coarse attention items)
# baseline (speedup 1.0000x reference)
; DI int otid() { int t = threadIdx.x & 255; asm volatile("" : "+v"(t)); return t; }
; DI void scan_item(const Params& p, int item) {
;     const int chain = item / 9, wd = (item % 9) * THREADS + otid();
;     if (wd >= STSZ / 2) return;
; DI void run_phase(int ph, char* smem) {
;     ...
;         for (int it = bid; it < 64 * 9; it += G) scan_item(p, it);
.LBB0_129:
	s_andn2_b64 vcc, exec, s[0:1]
	s_cbranch_vccnz .LBB0_199
	v_readlane_b32 s0, v253, 2
	s_mov_b64 s[30:31], s[50:51]
	s_cmpk_gt_i32 s0, 0x23f
	s_mov_b32 s14, 0x10000
	s_cbranch_scc1 .LBB0_136
	s_add_u32 s6, s68, 0x16580
	s_addc_u32 s7, s69, 0
	s_add_u32 s8, s70, 0x54
	s_addc_u32 s9, s71, 0
	v_readlane_b32 s10, v253, 2
	v_readlane_b32 s0, v253, 5
	s_addk_i32 s10, 0x40
	s_cmp_ge_i32 s10, s0
	s_cselect_b32 s1, s0, 0
	s_sub_i32 s10, s10, s1
	s_branch .LBB0_133
